# selection ranking count split between the two waves of a head pair (4 candidate groups each), partial masks exchanged through LDS
# speedup vs baseline: 1.0094x; 1.0094x over previous
; DI void attn_phase(const Params& p, const int layer, const int wid_s) {
;     ...
; #pragma unroll
;         for (int dt = 0; dt < 4; ++dt)
; #pragma unroll
;           for (int j = 0; j < 4; ++j) fin[(hp * 16 + dt * 4 + j) * 64] = o[dt][j] * gate_c;
;       }
;       unsigned mk = (2u << cur) - 1u;
;       if (cur >= 8) {
;       float impv[8];
;       __syncthreads();
; #pragma unroll
;       for (int nt = 0; nt < 8; ++nt) {
;         const float mine = impx[(wave * 8 + nt) * 64], other = impx[((wave ^ 4) * 8 + nt) * 64];
;         const float im = hpair == 0 ? mine + other : other + mine;
;         const int jb = nt * 4 + fql;
;         const bool forced = (jb == 0) || (jb == cur) || (jb == cur - 1);
;         impv[nt] = jb <= cur ? im + (forced ? 1e6f : 0.f) : NEGF;
;         impb[jb] = impv[nt];
;       }
.LBB0_332:
	v_cvt_f32_f16_sdwa v0, v121 dst_sel:DWORD dst_unused:UNUSED_PAD src0_sel:WORD_1
	v_mul_f32_e32 v0, 0xbfb8aa3b, v0
	v_exp_f32_e32 v0, v0
	s_nop 0
	v_add_f32_e32 v0, 1.0, v0
	v_div_scale_f32 v2, s[4:5], v0, v0, 1.0
	v_rcp_f32_e32 v3, v2
	v_div_scale_f32 v5, vcc, 1.0, v0, 1.0
	s_lshl_b32 s4, 2, s54
	v_fma_f32 v6, -v2, v3, 1.0
	v_fmac_f32_e32 v3, v6, v3
	v_mul_f32_e32 v6, v5, v3
	v_fma_f32 v7, -v2, v6, v5
	v_fmac_f32_e32 v6, v7, v3
	v_fma_f32 v2, -v2, v6, v5
	v_div_fmas_f32 v2, v2, v3, v6
	v_div_fixup_f32 v0, v2, v0, 1.0
	v_mul_f32_e32 v2, v0, v36
	v_mul_f32_e32 v3, v0, v37
	v_mul_f32_e32 v5, v0, v38
	v_mul_f32_e32 v6, v0, v39
	v_mul_f32_e32 v7, v0, v28
	ds_write2st64_b32 v188, v2, v3 offset0:168 offset1:169
	ds_write2st64_b32 v188, v5, v6 offset0:170 offset1:171
	v_mul_f32_e32 v2, v0, v29
	ds_write2st64_b32 v188, v7, v2 offset0:172 offset1:173
	v_mul_f32_e32 v2, v0, v30
	v_mul_f32_e32 v3, v0, v31
	ds_write2st64_b32 v188, v2, v3 offset0:174 offset1:175
	v_mul_f32_e32 v2, v0, v32
	v_mul_f32_e32 v3, v0, v33
	ds_write2st64_b32 v188, v2, v3 offset0:176 offset1:177
	v_mul_f32_e32 v2, v0, v34
	v_mul_f32_e32 v3, v0, v35
	ds_write2st64_b32 v188, v2, v3 offset0:178 offset1:179
	v_mul_f32_e32 v2, v0, v24
	v_mul_f32_e32 v3, v0, v25
	s_add_i32 s4, s4, -1
	ds_write2st64_b32 v188, v2, v3 offset0:180 offset1:181
	v_mul_f32_e32 v2, v0, v26
	v_mul_f32_e32 v0, v0, v27
	s_and_b64 vcc, exec, s[0:1]
	v_mov_b32_e32 v5, s4
	ds_write2st64_b32 v188, v2, v0 offset0:182 offset1:183
	s_cbranch_vccnz .LBB0_334
	s_waitcnt lgkmcnt(0)
	s_barrier
	ds_read_b32 v198, v151 offset:22656
	ds_read_b32 v199, v151 offset:22912
	ds_read_b32 v200, v151 offset:23168
	ds_read_b32 v201, v151 offset:23424
	ds_read_b32 v202, v151 offset:23680
	ds_read_b32 v203, v151 offset:23936
	ds_read_b32 v204, v151 offset:24192
	ds_read_b32 v205, v151 offset:24448
	ds_read_b32 v206, v182 offset:22656
	ds_read_b32 v207, v182 offset:22912
	ds_read_b32 v208, v182 offset:23168
	ds_read_b32 v209, v182 offset:23424
	ds_read_b32 v210, v182 offset:23680
	ds_read_b32 v211, v182 offset:23936
	ds_read_b32 v212, v182 offset:24192
	ds_read_b32 v213, v182 offset:24448
	s_add_i32 s6, s54, -1
	v_lshl_add_u32 v24, v123, 2, v147
	v_add_u32_e32 v238, 0, v123
	v_add_u32_e32 v239, 4, v123
	v_add_u32_e32 v240, 8, v123
	v_add_u32_e32 v241, 12, v123
	v_add_u32_e32 v242, 16, v123
	v_add_u32_e32 v243, 20, v123
	v_add_u32_e32 v244, 24, v123
	v_add_u32_e32 v245, 28, v123
	s_waitcnt lgkmcnt(0)
	v_cmp_eq_u32_e64 s[8:9], 0, v238
	v_cmp_eq_u32_e64 s[10:11], s54, v238
	v_cmp_eq_u32_e64 s[12:13], s6, v238
	v_add_f32_e32 v198, v198, v206
	s_or_b64 s[8:9], s[8:9], s[10:11]
	s_or_b64 s[8:9], s[8:9], s[12:13]
	v_cmp_lt_i32_e64 s[14:15], s54, v238
	s_nop 0
	v_cndmask_b32_e64 v0, 0, v159, s[8:9]
	s_nop 0
	v_add_f32_e32 v198, v0, v198
	v_cndmask_b32_e64 v39, v198, v4, s[14:15]
	ds_write_b32 v24, v39 offset:4224
	v_cmp_eq_u32_e64 s[8:9], 0, v239
	v_cmp_eq_u32_e64 s[10:11], s54, v239
	v_cmp_eq_u32_e64 s[12:13], s6, v239
	v_add_f32_e32 v199, v199, v207
	s_or_b64 s[8:9], s[8:9], s[10:11]
	s_or_b64 s[8:9], s[8:9], s[12:13]
	v_cmp_lt_i32_e64 s[14:15], s54, v239
	s_nop 0
	v_cndmask_b32_e64 v0, 0, v159, s[8:9]
	s_nop 0
	v_add_f32_e32 v199, v0, v199
	v_cndmask_b32_e64 v40, v199, v4, s[14:15]
	ds_write_b32 v24, v40 offset:4240
	v_cmp_eq_u32_e64 s[8:9], 0, v240
	v_cmp_eq_u32_e64 s[10:11], s54, v240
	v_cmp_eq_u32_e64 s[12:13], s6, v240
	v_add_f32_e32 v200, v200, v208
	s_or_b64 s[8:9], s[8:9], s[10:11]
	s_or_b64 s[8:9], s[8:9], s[12:13]
	v_cmp_lt_i32_e64 s[14:15], s54, v240
	s_nop 0
	v_cndmask_b32_e64 v0, 0, v159, s[8:9]
	s_nop 0
	v_add_f32_e32 v200, v0, v200
	v_cndmask_b32_e64 v38, v200, v4, s[14:15]
	ds_write_b32 v24, v38 offset:4256
	v_cmp_eq_u32_e64 s[8:9], 0, v241
	v_cmp_eq_u32_e64 s[10:11], s54, v241
	v_cmp_eq_u32_e64 s[12:13], s6, v241
	v_add_f32_e32 v201, v201, v209
	s_or_b64 s[8:9], s[8:9], s[10:11]
	s_or_b64 s[8:9], s[8:9], s[12:13]
	v_cmp_lt_i32_e64 s[14:15], s54, v241
	s_nop 0
	v_cndmask_b32_e64 v0, 0, v159, s[8:9]
	s_nop 0
	v_add_f32_e32 v201, v0, v201
	v_cndmask_b32_e64 v37, v201, v4, s[14:15]
	ds_write_b32 v24, v37 offset:4272
	v_cmp_eq_u32_e64 s[8:9], 0, v242
	v_cmp_eq_u32_e64 s[10:11], s54, v242
	v_cmp_eq_u32_e64 s[12:13], s6, v242
	v_add_f32_e32 v202, v202, v210
	s_or_b64 s[8:9], s[8:9], s[10:11]
	s_or_b64 s[8:9], s[8:9], s[12:13]
	v_cmp_lt_i32_e64 s[14:15], s54, v242
	s_nop 0
	v_cndmask_b32_e64 v0, 0, v159, s[8:9]
	s_nop 0
	v_add_f32_e32 v202, v0, v202
	v_cndmask_b32_e64 v36, v202, v4, s[14:15]
	ds_write_b32 v24, v36 offset:4288
	v_cmp_eq_u32_e64 s[8:9], 0, v243
	v_cmp_eq_u32_e64 s[10:11], s54, v243
	v_cmp_eq_u32_e64 s[12:13], s6, v243
	v_add_f32_e32 v203, v203, v211
	s_or_b64 s[8:9], s[8:9], s[10:11]
	s_or_b64 s[8:9], s[8:9], s[12:13]
	v_cmp_lt_i32_e64 s[14:15], s54, v243
	s_nop 0
	v_cndmask_b32_e64 v0, 0, v159, s[8:9]
	s_nop 0
	v_add_f32_e32 v203, v0, v203
	v_cndmask_b32_e64 v35, v203, v4, s[14:15]
	ds_write_b32 v24, v35 offset:4304
	v_cmp_eq_u32_e64 s[8:9], 0, v244
	v_cmp_eq_u32_e64 s[10:11], s54, v244
	v_cmp_eq_u32_e64 s[12:13], s6, v244
	v_add_f32_e32 v204, v204, v212
	s_or_b64 s[8:9], s[8:9], s[10:11]
	s_or_b64 s[8:9], s[8:9], s[12:13]
	v_cmp_lt_i32_e64 s[14:15], s54, v244
	s_nop 0
	v_cndmask_b32_e64 v0, 0, v159, s[8:9]
	s_nop 0
	v_add_f32_e32 v204, v0, v204
	v_cndmask_b32_e64 v34, v204, v4, s[14:15]
	ds_write_b32 v24, v34 offset:4320
	v_cmp_eq_u32_e64 s[8:9], 0, v245
	v_cmp_eq_u32_e64 s[10:11], s54, v245
	v_cmp_eq_u32_e64 s[12:13], s6, v245
	v_add_f32_e32 v205, v205, v213
	s_or_b64 s[8:9], s[8:9], s[10:11]
	s_or_b64 s[8:9], s[8:9], s[12:13]
	v_cmp_lt_i32_e64 s[14:15], s54, v245
	s_nop 0
	v_cndmask_b32_e64 v0, 0, v159, s[8:9]
	s_nop 0
	v_add_f32_e32 v205, v0, v205
	v_cndmask_b32_e64 v33, v205, v4, s[14:15]
	ds_write_b32 v24, v33 offset:4336
	s_waitcnt lgkmcnt(0)
	s_barrier
; #define LAS __attribute__((address_space(3)))
; DI void attn_phase(const Params& p, const int layer, const int wid_s) {
;     ...
;       int cnt[8];
; #pragma unroll
;       for (int nt = 0; nt < 8; ++nt) cnt[nt] = 0;
; #pragma unroll
;       for (int i = 0; i < 8; ++i) {
;         const f32x4 r4 = *(const LAS f32x4*)(impb + 4 * i);
;         const float rv[4] = {r4[0], r4[1], r4[2], r4[3]};
; #pragma unroll
;         for (int nt = 0; nt < 8; ++nt) {
;           const float a = impv[nt]; const int ja = nt * 4 + fql;
; #pragma unroll
;           for (int c = 0; c < 4; ++c) cnt[nt] += (int)(rv[c] > a) | ((int)(rv[c] == a) & (int)((4 * i + c) < ja));
;         }
;       }
	ds_read_b128 v[198:201], v147 offset:4224
	ds_read_b128 v[202:205], v147 offset:4240
	ds_read_b128 v[206:209], v147 offset:4256
	ds_read_b128 v[210:213], v147 offset:4272
	ds_read_b128 v[214:217], v147 offset:4288
	ds_read_b128 v[218:221], v147 offset:4304
	ds_read_b128 v[222:225], v147 offset:4320
	ds_read_b128 v[226:229], v147 offset:4336
	v_cmp_lt_i32_e64 s[6:7], 0, v123
	v_cmp_lt_i32_e64 s[8:9], 1, v123
	v_cmp_lt_i32_e64 s[10:11], 2, v123
	v_mov_b32_e32 v230, 0
	v_mov_b32_e32 v231, 0
	v_mov_b32_e32 v232, 0
	v_mov_b32_e32 v233, 0
	v_mov_b32_e32 v234, 0
	v_mov_b32_e32 v235, 0
	v_mov_b32_e32 v236, 0
	v_mov_b32_e32 v237, 0
	s_waitcnt lgkmcnt(0)
	s_and_b64 vcc, exec, s[30:31]
	s_cbranch_vccz .Lrk_lo
	v_cmp_ge_f32_e64 s[12:13], v198, v36
	v_cmp_ge_f32_e64 s[14:15], v199, v36
	v_cmp_ge_f32_e64 s[16:17], v200, v36
	v_addc_co_u32_e64 v234, s[18:19], 0, v234, s[12:13]
	v_cmp_ge_f32_e64 s[12:13], v201, v36
	v_addc_co_u32_e64 v234, s[18:19], 0, v234, s[14:15]
	v_cmp_ge_f32_e64 s[14:15], v202, v36
	v_addc_co_u32_e64 v234, s[18:19], 0, v234, s[16:17]
	v_cmp_ge_f32_e64 s[16:17], v203, v36
	v_addc_co_u32_e64 v234, s[18:19], 0, v234, s[12:13]
	v_cmp_ge_f32_e64 s[12:13], v204, v36
	v_addc_co_u32_e64 v234, s[18:19], 0, v234, s[14:15]
	v_cmp_ge_f32_e64 s[14:15], v205, v36
	v_addc_co_u32_e64 v234, s[18:19], 0, v234, s[16:17]
	v_cmp_ge_f32_e64 s[16:17], v206, v36
	v_addc_co_u32_e64 v234, s[18:19], 0, v234, s[12:13]
	v_cmp_ge_f32_e64 s[12:13], v207, v36
	v_addc_co_u32_e64 v234, s[18:19], 0, v234, s[14:15]
	v_cmp_ge_f32_e64 s[14:15], v208, v36
	v_addc_co_u32_e64 v234, s[18:19], 0, v234, s[16:17]
	v_cmp_ge_f32_e64 s[16:17], v209, v36
	v_addc_co_u32_e64 v234, s[18:19], 0, v234, s[12:13]
	v_cmp_ge_f32_e64 s[12:13], v210, v36
	v_addc_co_u32_e64 v234, s[18:19], 0, v234, s[14:15]
	v_cmp_ge_f32_e64 s[14:15], v211, v36
	v_addc_co_u32_e64 v234, s[18:19], 0, v234, s[16:17]
	v_cmp_ge_f32_e64 s[16:17], v212, v36
	v_addc_co_u32_e64 v234, s[18:19], 0, v234, s[12:13]
	v_cmp_ge_f32_e64 s[12:13], v213, v36
	v_addc_co_u32_e64 v234, s[18:19], 0, v234, s[14:15]
	v_cmp_gt_f32_e64 s[14:15], v214, v36
	v_cmp_ge_f32_e64 s[20:21], v214, v36
	s_and_b64 s[20:21], s[20:21], s[6:7]
	s_or_b64 s[14:15], s[14:15], s[20:21]
	v_addc_co_u32_e64 v234, s[18:19], 0, v234, s[16:17]
	v_cmp_gt_f32_e64 s[16:17], v215, v36
	v_cmp_ge_f32_e64 s[20:21], v215, v36
	s_and_b64 s[20:21], s[20:21], s[8:9]
	s_or_b64 s[16:17], s[16:17], s[20:21]
	v_addc_co_u32_e64 v234, s[18:19], 0, v234, s[12:13]
	v_cmp_gt_f32_e64 s[12:13], v216, v36
	v_cmp_ge_f32_e64 s[20:21], v216, v36
	s_and_b64 s[20:21], s[20:21], s[10:11]
	s_or_b64 s[12:13], s[12:13], s[20:21]
	v_addc_co_u32_e64 v234, s[18:19], 0, v234, s[14:15]
	v_cmp_gt_f32_e64 s[14:15], v217, v36
	v_addc_co_u32_e64 v234, s[18:19], 0, v234, s[16:17]
	v_cmp_gt_f32_e64 s[16:17], v218, v36
	v_addc_co_u32_e64 v234, s[18:19], 0, v234, s[12:13]
	v_cmp_gt_f32_e64 s[12:13], v219, v36
	v_addc_co_u32_e64 v234, s[18:19], 0, v234, s[14:15]
	v_cmp_gt_f32_e64 s[14:15], v220, v36
	v_addc_co_u32_e64 v234, s[18:19], 0, v234, s[16:17]
	v_cmp_gt_f32_e64 s[16:17], v221, v36
	v_addc_co_u32_e64 v234, s[18:19], 0, v234, s[12:13]
	v_cmp_gt_f32_e64 s[12:13], v222, v36
	v_addc_co_u32_e64 v234, s[18:19], 0, v234, s[14:15]
	v_cmp_gt_f32_e64 s[14:15], v223, v36
	v_addc_co_u32_e64 v234, s[18:19], 0, v234, s[16:17]
	v_cmp_gt_f32_e64 s[16:17], v224, v36
	v_addc_co_u32_e64 v234, s[18:19], 0, v234, s[12:13]
	v_cmp_gt_f32_e64 s[12:13], v225, v36
	v_addc_co_u32_e64 v234, s[18:19], 0, v234, s[14:15]
	v_cmp_gt_f32_e64 s[14:15], v226, v36
	v_addc_co_u32_e64 v234, s[18:19], 0, v234, s[16:17]
	v_cmp_gt_f32_e64 s[16:17], v227, v36
	v_addc_co_u32_e64 v234, s[18:19], 0, v234, s[12:13]
	v_cmp_gt_f32_e64 s[12:13], v228, v36
	v_addc_co_u32_e64 v234, s[18:19], 0, v234, s[14:15]
	v_cmp_gt_f32_e64 s[14:15], v229, v36
	v_addc_co_u32_e64 v234, s[18:19], 0, v234, s[16:17]
	v_cmp_ge_f32_e64 s[16:17], v198, v35
	v_addc_co_u32_e64 v234, s[18:19], 0, v234, s[12:13]
	v_cmp_ge_f32_e64 s[12:13], v199, v35
	v_addc_co_u32_e64 v234, s[18:19], 0, v234, s[14:15]
	v_cmp_ge_f32_e64 s[14:15], v200, v35
	v_addc_co_u32_e64 v235, s[18:19], 0, v235, s[16:17]
	v_cmp_ge_f32_e64 s[16:17], v201, v35
	v_addc_co_u32_e64 v235, s[18:19], 0, v235, s[12:13]
	v_cmp_ge_f32_e64 s[12:13], v202, v35
	v_addc_co_u32_e64 v235, s[18:19], 0, v235, s[14:15]
	v_cmp_ge_f32_e64 s[14:15], v203, v35
	v_addc_co_u32_e64 v235, s[18:19], 0, v235, s[16:17]
	v_cmp_ge_f32_e64 s[16:17], v204, v35
	v_addc_co_u32_e64 v235, s[18:19], 0, v235, s[12:13]
	v_cmp_ge_f32_e64 s[12:13], v205, v35
	v_addc_co_u32_e64 v235, s[18:19], 0, v235, s[14:15]
	v_cmp_ge_f32_e64 s[14:15], v206, v35
	v_addc_co_u32_e64 v235, s[18:19], 0, v235, s[16:17]
	v_cmp_ge_f32_e64 s[16:17], v207, v35
	v_addc_co_u32_e64 v235, s[18:19], 0, v235, s[12:13]
	v_cmp_ge_f32_e64 s[12:13], v208, v35
	v_addc_co_u32_e64 v235, s[18:19], 0, v235, s[14:15]
	v_cmp_ge_f32_e64 s[14:15], v209, v35
	v_addc_co_u32_e64 v235, s[18:19], 0, v235, s[16:17]
	v_cmp_ge_f32_e64 s[16:17], v210, v35
	v_addc_co_u32_e64 v235, s[18:19], 0, v235, s[12:13]
	v_cmp_ge_f32_e64 s[12:13], v211, v35
	v_addc_co_u32_e64 v235, s[18:19], 0, v235, s[14:15]
	v_cmp_ge_f32_e64 s[14:15], v212, v35
	v_addc_co_u32_e64 v235, s[18:19], 0, v235, s[16:17]
	v_cmp_ge_f32_e64 s[16:17], v213, v35
	v_addc_co_u32_e64 v235, s[18:19], 0, v235, s[12:13]
	v_cmp_ge_f32_e64 s[12:13], v214, v35
	v_addc_co_u32_e64 v235, s[18:19], 0, v235, s[14:15]
	v_cmp_ge_f32_e64 s[14:15], v215, v35
	v_addc_co_u32_e64 v235, s[18:19], 0, v235, s[16:17]
	v_cmp_ge_f32_e64 s[16:17], v216, v35
	v_addc_co_u32_e64 v235, s[18:19], 0, v235, s[12:13]
	v_cmp_ge_f32_e64 s[12:13], v217, v35
; #define LAS __attribute__((address_space(3)))
; DI void attn_phase(const Params& p, const int layer, const int wid_s) {
;     ...
;       for (int i = 0; i < 8; ++i) {
;         const f32x4 r4 = *(const LAS f32x4*)(impb + 4 * i);
;         const float rv[4] = {r4[0], r4[1], r4[2], r4[3]};
; #pragma unroll
;         for (int nt = 0; nt < 8; ++nt) {
;           const float a = impv[nt]; const int ja = nt * 4 + fql;
; #pragma unroll
;           for (int c = 0; c < 4; ++c) cnt[nt] += (int)(rv[c] > a) | ((int)(rv[c] == a) & (int)((4 * i + c) < ja));
;         }
;       }
	v_addc_co_u32_e64 v235, s[18:19], 0, v235, s[14:15]
	v_cmp_gt_f32_e64 s[14:15], v218, v35
	v_cmp_ge_f32_e64 s[20:21], v218, v35
	s_and_b64 s[20:21], s[20:21], s[6:7]
	s_or_b64 s[14:15], s[14:15], s[20:21]
	v_addc_co_u32_e64 v235, s[18:19], 0, v235, s[16:17]
	v_cmp_gt_f32_e64 s[16:17], v219, v35
	v_cmp_ge_f32_e64 s[20:21], v219, v35
	s_and_b64 s[20:21], s[20:21], s[8:9]
	s_or_b64 s[16:17], s[16:17], s[20:21]
	v_addc_co_u32_e64 v235, s[18:19], 0, v235, s[12:13]
	v_cmp_gt_f32_e64 s[12:13], v220, v35
	v_cmp_ge_f32_e64 s[20:21], v220, v35
	s_and_b64 s[20:21], s[20:21], s[10:11]
	s_or_b64 s[12:13], s[12:13], s[20:21]
	v_addc_co_u32_e64 v235, s[18:19], 0, v235, s[14:15]
	v_cmp_gt_f32_e64 s[14:15], v221, v35
	v_addc_co_u32_e64 v235, s[18:19], 0, v235, s[16:17]
	v_cmp_gt_f32_e64 s[16:17], v222, v35
	v_addc_co_u32_e64 v235, s[18:19], 0, v235, s[12:13]
	v_cmp_gt_f32_e64 s[12:13], v223, v35
	v_addc_co_u32_e64 v235, s[18:19], 0, v235, s[14:15]
	v_cmp_gt_f32_e64 s[14:15], v224, v35
	v_addc_co_u32_e64 v235, s[18:19], 0, v235, s[16:17]
	v_cmp_gt_f32_e64 s[16:17], v225, v35
	v_addc_co_u32_e64 v235, s[18:19], 0, v235, s[12:13]
	v_cmp_gt_f32_e64 s[12:13], v226, v35
	v_addc_co_u32_e64 v235, s[18:19], 0, v235, s[14:15]
	v_cmp_gt_f32_e64 s[14:15], v227, v35
	v_addc_co_u32_e64 v235, s[18:19], 0, v235, s[16:17]
	v_cmp_gt_f32_e64 s[16:17], v228, v35
	v_addc_co_u32_e64 v235, s[18:19], 0, v235, s[12:13]
	v_cmp_gt_f32_e64 s[12:13], v229, v35
	v_addc_co_u32_e64 v235, s[18:19], 0, v235, s[14:15]
	v_cmp_ge_f32_e64 s[14:15], v198, v34
	v_addc_co_u32_e64 v235, s[18:19], 0, v235, s[16:17]
	v_cmp_ge_f32_e64 s[16:17], v199, v34
	v_addc_co_u32_e64 v235, s[18:19], 0, v235, s[12:13]
	v_cmp_ge_f32_e64 s[12:13], v200, v34
	v_addc_co_u32_e64 v236, s[18:19], 0, v236, s[14:15]
	v_cmp_ge_f32_e64 s[14:15], v201, v34
	v_addc_co_u32_e64 v236, s[18:19], 0, v236, s[16:17]
	v_cmp_ge_f32_e64 s[16:17], v202, v34
	v_addc_co_u32_e64 v236, s[18:19], 0, v236, s[12:13]
	v_cmp_ge_f32_e64 s[12:13], v203, v34
	v_addc_co_u32_e64 v236, s[18:19], 0, v236, s[14:15]
	v_cmp_ge_f32_e64 s[14:15], v204, v34
	v_addc_co_u32_e64 v236, s[18:19], 0, v236, s[16:17]
	v_cmp_ge_f32_e64 s[16:17], v205, v34
	v_addc_co_u32_e64 v236, s[18:19], 0, v236, s[12:13]
	v_cmp_ge_f32_e64 s[12:13], v206, v34
	v_addc_co_u32_e64 v236, s[18:19], 0, v236, s[14:15]
	v_cmp_ge_f32_e64 s[14:15], v207, v34
	v_addc_co_u32_e64 v236, s[18:19], 0, v236, s[16:17]
	v_cmp_ge_f32_e64 s[16:17], v208, v34
	v_addc_co_u32_e64 v236, s[18:19], 0, v236, s[12:13]
	v_cmp_ge_f32_e64 s[12:13], v209, v34
	v_addc_co_u32_e64 v236, s[18:19], 0, v236, s[14:15]
	v_cmp_ge_f32_e64 s[14:15], v210, v34
	v_addc_co_u32_e64 v236, s[18:19], 0, v236, s[16:17]
	v_cmp_ge_f32_e64 s[16:17], v211, v34
	v_addc_co_u32_e64 v236, s[18:19], 0, v236, s[12:13]
	v_cmp_ge_f32_e64 s[12:13], v212, v34
	v_addc_co_u32_e64 v236, s[18:19], 0, v236, s[14:15]
	v_cmp_ge_f32_e64 s[14:15], v213, v34
	v_addc_co_u32_e64 v236, s[18:19], 0, v236, s[16:17]
	v_cmp_ge_f32_e64 s[16:17], v214, v34
	v_addc_co_u32_e64 v236, s[18:19], 0, v236, s[12:13]
	v_cmp_ge_f32_e64 s[12:13], v215, v34
	v_addc_co_u32_e64 v236, s[18:19], 0, v236, s[14:15]
	v_cmp_ge_f32_e64 s[14:15], v216, v34
	v_addc_co_u32_e64 v236, s[18:19], 0, v236, s[16:17]
	v_cmp_ge_f32_e64 s[16:17], v217, v34
	v_addc_co_u32_e64 v236, s[18:19], 0, v236, s[12:13]
	v_cmp_ge_f32_e64 s[12:13], v218, v34
	v_addc_co_u32_e64 v236, s[18:19], 0, v236, s[14:15]
	v_cmp_ge_f32_e64 s[14:15], v219, v34
	v_addc_co_u32_e64 v236, s[18:19], 0, v236, s[16:17]
	v_cmp_ge_f32_e64 s[16:17], v220, v34
	v_addc_co_u32_e64 v236, s[18:19], 0, v236, s[12:13]
	v_cmp_ge_f32_e64 s[12:13], v221, v34
	v_addc_co_u32_e64 v236, s[18:19], 0, v236, s[14:15]
	v_cmp_gt_f32_e64 s[14:15], v222, v34
	v_cmp_ge_f32_e64 s[20:21], v222, v34
	s_and_b64 s[20:21], s[20:21], s[6:7]
	s_or_b64 s[14:15], s[14:15], s[20:21]
	v_addc_co_u32_e64 v236, s[18:19], 0, v236, s[16:17]
	v_cmp_gt_f32_e64 s[16:17], v223, v34
	v_cmp_ge_f32_e64 s[20:21], v223, v34
	s_and_b64 s[20:21], s[20:21], s[8:9]
	s_or_b64 s[16:17], s[16:17], s[20:21]
	v_addc_co_u32_e64 v236, s[18:19], 0, v236, s[12:13]
	v_cmp_gt_f32_e64 s[12:13], v224, v34
	v_cmp_ge_f32_e64 s[20:21], v224, v34
	s_and_b64 s[20:21], s[20:21], s[10:11]
	s_or_b64 s[12:13], s[12:13], s[20:21]
	v_addc_co_u32_e64 v236, s[18:19], 0, v236, s[14:15]
	v_cmp_gt_f32_e64 s[14:15], v225, v34
	v_addc_co_u32_e64 v236, s[18:19], 0, v236, s[16:17]
	v_cmp_gt_f32_e64 s[16:17], v226, v34
	v_addc_co_u32_e64 v236, s[18:19], 0, v236, s[12:13]
	v_cmp_gt_f32_e64 s[12:13], v227, v34
	v_addc_co_u32_e64 v236, s[18:19], 0, v236, s[14:15]
	v_cmp_gt_f32_e64 s[14:15], v228, v34
	v_addc_co_u32_e64 v236, s[18:19], 0, v236, s[16:17]
	v_cmp_gt_f32_e64 s[16:17], v229, v34
	v_addc_co_u32_e64 v236, s[18:19], 0, v236, s[12:13]
	v_cmp_ge_f32_e64 s[12:13], v198, v33
	v_addc_co_u32_e64 v236, s[18:19], 0, v236, s[14:15]
	v_cmp_ge_f32_e64 s[14:15], v199, v33
	v_addc_co_u32_e64 v236, s[18:19], 0, v236, s[16:17]
	v_cmp_ge_f32_e64 s[16:17], v200, v33
	v_addc_co_u32_e64 v237, s[18:19], 0, v237, s[12:13]
	v_cmp_ge_f32_e64 s[12:13], v201, v33
	v_addc_co_u32_e64 v237, s[18:19], 0, v237, s[14:15]
	v_cmp_ge_f32_e64 s[14:15], v202, v33
	v_addc_co_u32_e64 v237, s[18:19], 0, v237, s[16:17]
	v_cmp_ge_f32_e64 s[16:17], v203, v33
	v_addc_co_u32_e64 v237, s[18:19], 0, v237, s[12:13]
	v_cmp_ge_f32_e64 s[12:13], v204, v33
	v_addc_co_u32_e64 v237, s[18:19], 0, v237, s[14:15]
	v_cmp_ge_f32_e64 s[14:15], v205, v33
	v_addc_co_u32_e64 v237, s[18:19], 0, v237, s[16:17]
	v_cmp_ge_f32_e64 s[16:17], v206, v33
	v_addc_co_u32_e64 v237, s[18:19], 0, v237, s[12:13]
	v_cmp_ge_f32_e64 s[12:13], v207, v33
	v_addc_co_u32_e64 v237, s[18:19], 0, v237, s[14:15]
; #define LAS __attribute__((address_space(3)))
; DI void attn_phase(const Params& p, const int layer, const int wid_s) {
;     ...
;       for (int i = 0; i < 8; ++i) {
;         const f32x4 r4 = *(const LAS f32x4*)(impb + 4 * i);
;         const float rv[4] = {r4[0], r4[1], r4[2], r4[3]};
; #pragma unroll
;         for (int nt = 0; nt < 8; ++nt) {
;           const float a = impv[nt]; const int ja = nt * 4 + fql;
; #pragma unroll
;           for (int c = 0; c < 4; ++c) cnt[nt] += (int)(rv[c] > a) | ((int)(rv[c] == a) & (int)((4 * i + c) < ja));
;         }
;       }
;       mk = 0;
; #pragma unroll
;       for (int nt = 0; nt < 8; ++nt) { const int ja = nt * 4 + fql; if (cnt[nt] < 8 && ja <= cur) mk |= 1u << ja; }
	v_cmp_ge_f32_e64 s[14:15], v208, v33
	v_addc_co_u32_e64 v237, s[18:19], 0, v237, s[16:17]
	v_cmp_ge_f32_e64 s[16:17], v209, v33
	v_addc_co_u32_e64 v237, s[18:19], 0, v237, s[12:13]
	v_cmp_ge_f32_e64 s[12:13], v210, v33
	v_addc_co_u32_e64 v237, s[18:19], 0, v237, s[14:15]
	v_cmp_ge_f32_e64 s[14:15], v211, v33
	v_addc_co_u32_e64 v237, s[18:19], 0, v237, s[16:17]
	v_cmp_ge_f32_e64 s[16:17], v212, v33
	v_addc_co_u32_e64 v237, s[18:19], 0, v237, s[12:13]
	v_cmp_ge_f32_e64 s[12:13], v213, v33
	v_addc_co_u32_e64 v237, s[18:19], 0, v237, s[14:15]
	v_cmp_ge_f32_e64 s[14:15], v214, v33
	v_addc_co_u32_e64 v237, s[18:19], 0, v237, s[16:17]
	v_cmp_ge_f32_e64 s[16:17], v215, v33
	v_addc_co_u32_e64 v237, s[18:19], 0, v237, s[12:13]
	v_cmp_ge_f32_e64 s[12:13], v216, v33
	v_addc_co_u32_e64 v237, s[18:19], 0, v237, s[14:15]
	v_cmp_ge_f32_e64 s[14:15], v217, v33
	v_addc_co_u32_e64 v237, s[18:19], 0, v237, s[16:17]
	v_cmp_ge_f32_e64 s[16:17], v218, v33
	v_addc_co_u32_e64 v237, s[18:19], 0, v237, s[12:13]
	v_cmp_ge_f32_e64 s[12:13], v219, v33
	v_addc_co_u32_e64 v237, s[18:19], 0, v237, s[14:15]
	v_cmp_ge_f32_e64 s[14:15], v220, v33
	v_addc_co_u32_e64 v237, s[18:19], 0, v237, s[16:17]
	v_cmp_ge_f32_e64 s[16:17], v221, v33
	v_addc_co_u32_e64 v237, s[18:19], 0, v237, s[12:13]
	v_cmp_ge_f32_e64 s[12:13], v222, v33
	v_addc_co_u32_e64 v237, s[18:19], 0, v237, s[14:15]
	v_cmp_ge_f32_e64 s[14:15], v223, v33
	v_addc_co_u32_e64 v237, s[18:19], 0, v237, s[16:17]
	v_cmp_ge_f32_e64 s[16:17], v224, v33
	v_addc_co_u32_e64 v237, s[18:19], 0, v237, s[12:13]
	v_cmp_ge_f32_e64 s[12:13], v225, v33
	v_addc_co_u32_e64 v237, s[18:19], 0, v237, s[14:15]
	v_cmp_gt_f32_e64 s[14:15], v226, v33
	v_cmp_ge_f32_e64 s[20:21], v226, v33
	s_and_b64 s[20:21], s[20:21], s[6:7]
	s_or_b64 s[14:15], s[14:15], s[20:21]
	v_addc_co_u32_e64 v237, s[18:19], 0, v237, s[16:17]
	v_cmp_gt_f32_e64 s[16:17], v227, v33
	v_cmp_ge_f32_e64 s[20:21], v227, v33
	s_and_b64 s[20:21], s[20:21], s[8:9]
	s_or_b64 s[16:17], s[16:17], s[20:21]
	v_addc_co_u32_e64 v237, s[18:19], 0, v237, s[12:13]
	v_cmp_gt_f32_e64 s[12:13], v228, v33
	v_cmp_ge_f32_e64 s[20:21], v228, v33
	s_and_b64 s[20:21], s[20:21], s[10:11]
	s_or_b64 s[12:13], s[12:13], s[20:21]
	v_addc_co_u32_e64 v237, s[18:19], 0, v237, s[14:15]
	v_cmp_gt_f32_e64 s[14:15], v229, v33
	v_addc_co_u32_e64 v237, s[18:19], 0, v237, s[16:17]
	s_nop 1
	v_addc_co_u32_e64 v237, s[18:19], 0, v237, s[12:13]
	v_addc_co_u32_e64 v237, s[18:19], 0, v237, s[14:15]
	v_cmp_gt_u32_e64 s[12:13], 8, v234
	v_cmp_ge_i32_e64 s[14:15], s54, v242
	v_lshlrev_b32_e64 v242, v242, 1
	s_and_b64 s[12:13], s[12:13], s[14:15]
	s_nop 1
	v_cndmask_b32_e64 v242, 0, v242, s[12:13]
	v_cmp_gt_u32_e64 s[16:17], 8, v235
	v_cmp_ge_i32_e64 s[20:21], s54, v243
	v_lshlrev_b32_e64 v243, v243, 1
	s_and_b64 s[16:17], s[16:17], s[20:21]
	s_nop 1
	v_cndmask_b32_e64 v243, 0, v243, s[16:17]
	v_cmp_gt_u32_e64 s[12:13], 8, v236
	v_cmp_ge_i32_e64 s[14:15], s54, v244
	v_lshlrev_b32_e64 v244, v244, 1
	s_and_b64 s[12:13], s[12:13], s[14:15]
	s_nop 1
	v_cndmask_b32_e64 v244, 0, v244, s[12:13]
	v_cmp_gt_u32_e64 s[16:17], 8, v237
	v_cmp_ge_i32_e64 s[20:21], s54, v245
	v_lshlrev_b32_e64 v245, v245, 1
	s_and_b64 s[16:17], s[16:17], s[20:21]
	s_nop 1
	v_cndmask_b32_e64 v245, 0, v245, s[16:17]
	v_or_b32_e32 v0, v242, v243
	v_or3_b32 v0, v0, v244, v245
	s_branch .Lrk_join
.Lrk_lo:
	v_cmp_gt_f32_e64 s[12:13], v198, v39
	v_cmp_ge_f32_e64 s[20:21], v198, v39
	s_and_b64 s[20:21], s[20:21], s[6:7]
	s_or_b64 s[12:13], s[12:13], s[20:21]
	v_cmp_gt_f32_e64 s[14:15], v199, v39
	v_cmp_ge_f32_e64 s[20:21], v199, v39
	s_and_b64 s[20:21], s[20:21], s[8:9]
	s_or_b64 s[14:15], s[14:15], s[20:21]
	v_cmp_gt_f32_e64 s[16:17], v200, v39
	v_cmp_ge_f32_e64 s[20:21], v200, v39
	s_and_b64 s[20:21], s[20:21], s[10:11]
	s_or_b64 s[16:17], s[16:17], s[20:21]
	v_addc_co_u32_e64 v230, s[18:19], 0, v230, s[12:13]
	v_cmp_gt_f32_e64 s[12:13], v201, v39
	v_addc_co_u32_e64 v230, s[18:19], 0, v230, s[14:15]
	v_cmp_gt_f32_e64 s[14:15], v202, v39
	v_addc_co_u32_e64 v230, s[18:19], 0, v230, s[16:17]
	v_cmp_gt_f32_e64 s[16:17], v203, v39
	v_addc_co_u32_e64 v230, s[18:19], 0, v230, s[12:13]
	v_cmp_gt_f32_e64 s[12:13], v204, v39
	v_addc_co_u32_e64 v230, s[18:19], 0, v230, s[14:15]
	v_cmp_gt_f32_e64 s[14:15], v205, v39
	v_addc_co_u32_e64 v230, s[18:19], 0, v230, s[16:17]
	v_cmp_gt_f32_e64 s[16:17], v206, v39
	v_addc_co_u32_e64 v230, s[18:19], 0, v230, s[12:13]
	v_cmp_gt_f32_e64 s[12:13], v207, v39
	v_addc_co_u32_e64 v230, s[18:19], 0, v230, s[14:15]
	v_cmp_gt_f32_e64 s[14:15], v208, v39
	v_addc_co_u32_e64 v230, s[18:19], 0, v230, s[16:17]
	v_cmp_gt_f32_e64 s[16:17], v209, v39
	v_addc_co_u32_e64 v230, s[18:19], 0, v230, s[12:13]
	v_cmp_gt_f32_e64 s[12:13], v210, v39
	v_addc_co_u32_e64 v230, s[18:19], 0, v230, s[14:15]
	v_cmp_gt_f32_e64 s[14:15], v211, v39
	v_addc_co_u32_e64 v230, s[18:19], 0, v230, s[16:17]
	v_cmp_gt_f32_e64 s[16:17], v212, v39
	v_addc_co_u32_e64 v230, s[18:19], 0, v230, s[12:13]
	v_cmp_gt_f32_e64 s[12:13], v213, v39
	v_addc_co_u32_e64 v230, s[18:19], 0, v230, s[14:15]
	v_cmp_gt_f32_e64 s[14:15], v214, v39
	v_addc_co_u32_e64 v230, s[18:19], 0, v230, s[16:17]
	v_cmp_gt_f32_e64 s[16:17], v215, v39
	v_addc_co_u32_e64 v230, s[18:19], 0, v230, s[12:13]
	v_cmp_gt_f32_e64 s[12:13], v216, v39
	v_addc_co_u32_e64 v230, s[18:19], 0, v230, s[14:15]
	v_cmp_gt_f32_e64 s[14:15], v217, v39
	v_addc_co_u32_e64 v230, s[18:19], 0, v230, s[16:17]
	v_cmp_gt_f32_e64 s[16:17], v218, v39
	v_addc_co_u32_e64 v230, s[18:19], 0, v230, s[12:13]
	v_cmp_gt_f32_e64 s[12:13], v219, v39
	v_addc_co_u32_e64 v230, s[18:19], 0, v230, s[14:15]
	v_cmp_gt_f32_e64 s[14:15], v220, v39
; #define LAS __attribute__((address_space(3)))
; DI void attn_phase(const Params& p, const int layer, const int wid_s) {
;     ...
;       for (int i = 0; i < 8; ++i) {
;         const f32x4 r4 = *(const LAS f32x4*)(impb + 4 * i);
;         const float rv[4] = {r4[0], r4[1], r4[2], r4[3]};
; #pragma unroll
;         for (int nt = 0; nt < 8; ++nt) {
;           const float a = impv[nt]; const int ja = nt * 4 + fql;
; #pragma unroll
;           for (int c = 0; c < 4; ++c) cnt[nt] += (int)(rv[c] > a) | ((int)(rv[c] == a) & (int)((4 * i + c) < ja));
;         }
;       }
	v_addc_co_u32_e64 v230, s[18:19], 0, v230, s[16:17]
	v_cmp_gt_f32_e64 s[16:17], v221, v39
	v_addc_co_u32_e64 v230, s[18:19], 0, v230, s[12:13]
	v_cmp_gt_f32_e64 s[12:13], v222, v39
	v_addc_co_u32_e64 v230, s[18:19], 0, v230, s[14:15]
	v_cmp_gt_f32_e64 s[14:15], v223, v39
	v_addc_co_u32_e64 v230, s[18:19], 0, v230, s[16:17]
	v_cmp_gt_f32_e64 s[16:17], v224, v39
	v_addc_co_u32_e64 v230, s[18:19], 0, v230, s[12:13]
	v_cmp_gt_f32_e64 s[12:13], v225, v39
	v_addc_co_u32_e64 v230, s[18:19], 0, v230, s[14:15]
	v_cmp_gt_f32_e64 s[14:15], v226, v39
	v_addc_co_u32_e64 v230, s[18:19], 0, v230, s[16:17]
	v_cmp_gt_f32_e64 s[16:17], v227, v39
	v_addc_co_u32_e64 v230, s[18:19], 0, v230, s[12:13]
	v_cmp_gt_f32_e64 s[12:13], v228, v39
	v_addc_co_u32_e64 v230, s[18:19], 0, v230, s[14:15]
	v_cmp_gt_f32_e64 s[14:15], v229, v39
	v_addc_co_u32_e64 v230, s[18:19], 0, v230, s[16:17]
	v_cmp_ge_f32_e64 s[16:17], v198, v40
	v_addc_co_u32_e64 v230, s[18:19], 0, v230, s[12:13]
	v_cmp_ge_f32_e64 s[12:13], v199, v40
	v_addc_co_u32_e64 v230, s[18:19], 0, v230, s[14:15]
	v_cmp_ge_f32_e64 s[14:15], v200, v40
	v_addc_co_u32_e64 v231, s[18:19], 0, v231, s[16:17]
	v_cmp_ge_f32_e64 s[16:17], v201, v40
	v_addc_co_u32_e64 v231, s[18:19], 0, v231, s[12:13]
	v_cmp_gt_f32_e64 s[12:13], v202, v40
	v_cmp_ge_f32_e64 s[20:21], v202, v40
	s_and_b64 s[20:21], s[20:21], s[6:7]
	s_or_b64 s[12:13], s[12:13], s[20:21]
	v_addc_co_u32_e64 v231, s[18:19], 0, v231, s[14:15]
	v_cmp_gt_f32_e64 s[14:15], v203, v40
	v_cmp_ge_f32_e64 s[20:21], v203, v40
	s_and_b64 s[20:21], s[20:21], s[8:9]
	s_or_b64 s[14:15], s[14:15], s[20:21]
	v_addc_co_u32_e64 v231, s[18:19], 0, v231, s[16:17]
	v_cmp_gt_f32_e64 s[16:17], v204, v40
	v_cmp_ge_f32_e64 s[20:21], v204, v40
	s_and_b64 s[20:21], s[20:21], s[10:11]
	s_or_b64 s[16:17], s[16:17], s[20:21]
	v_addc_co_u32_e64 v231, s[18:19], 0, v231, s[12:13]
	v_cmp_gt_f32_e64 s[12:13], v205, v40
	v_addc_co_u32_e64 v231, s[18:19], 0, v231, s[14:15]
	v_cmp_gt_f32_e64 s[14:15], v206, v40
	v_addc_co_u32_e64 v231, s[18:19], 0, v231, s[16:17]
	v_cmp_gt_f32_e64 s[16:17], v207, v40
	v_addc_co_u32_e64 v231, s[18:19], 0, v231, s[12:13]
	v_cmp_gt_f32_e64 s[12:13], v208, v40
	v_addc_co_u32_e64 v231, s[18:19], 0, v231, s[14:15]
	v_cmp_gt_f32_e64 s[14:15], v209, v40
	v_addc_co_u32_e64 v231, s[18:19], 0, v231, s[16:17]
	v_cmp_gt_f32_e64 s[16:17], v210, v40
	v_addc_co_u32_e64 v231, s[18:19], 0, v231, s[12:13]
	v_cmp_gt_f32_e64 s[12:13], v211, v40
	v_addc_co_u32_e64 v231, s[18:19], 0, v231, s[14:15]
	v_cmp_gt_f32_e64 s[14:15], v212, v40
	v_addc_co_u32_e64 v231, s[18:19], 0, v231, s[16:17]
	v_cmp_gt_f32_e64 s[16:17], v213, v40
	v_addc_co_u32_e64 v231, s[18:19], 0, v231, s[12:13]
	v_cmp_gt_f32_e64 s[12:13], v214, v40
	v_addc_co_u32_e64 v231, s[18:19], 0, v231, s[14:15]
	v_cmp_gt_f32_e64 s[14:15], v215, v40
	v_addc_co_u32_e64 v231, s[18:19], 0, v231, s[16:17]
	v_cmp_gt_f32_e64 s[16:17], v216, v40
	v_addc_co_u32_e64 v231, s[18:19], 0, v231, s[12:13]
	v_cmp_gt_f32_e64 s[12:13], v217, v40
	v_addc_co_u32_e64 v231, s[18:19], 0, v231, s[14:15]
	v_cmp_gt_f32_e64 s[14:15], v218, v40
	v_addc_co_u32_e64 v231, s[18:19], 0, v231, s[16:17]
	v_cmp_gt_f32_e64 s[16:17], v219, v40
	v_addc_co_u32_e64 v231, s[18:19], 0, v231, s[12:13]
	v_cmp_gt_f32_e64 s[12:13], v220, v40
	v_addc_co_u32_e64 v231, s[18:19], 0, v231, s[14:15]
	v_cmp_gt_f32_e64 s[14:15], v221, v40
	v_addc_co_u32_e64 v231, s[18:19], 0, v231, s[16:17]
	v_cmp_gt_f32_e64 s[16:17], v222, v40
	v_addc_co_u32_e64 v231, s[18:19], 0, v231, s[12:13]
	v_cmp_gt_f32_e64 s[12:13], v223, v40
	v_addc_co_u32_e64 v231, s[18:19], 0, v231, s[14:15]
	v_cmp_gt_f32_e64 s[14:15], v224, v40
	v_addc_co_u32_e64 v231, s[18:19], 0, v231, s[16:17]
	v_cmp_gt_f32_e64 s[16:17], v225, v40
	v_addc_co_u32_e64 v231, s[18:19], 0, v231, s[12:13]
	v_cmp_gt_f32_e64 s[12:13], v226, v40
	v_addc_co_u32_e64 v231, s[18:19], 0, v231, s[14:15]
	v_cmp_gt_f32_e64 s[14:15], v227, v40
	v_addc_co_u32_e64 v231, s[18:19], 0, v231, s[16:17]
	v_cmp_gt_f32_e64 s[16:17], v228, v40
	v_addc_co_u32_e64 v231, s[18:19], 0, v231, s[12:13]
	v_cmp_gt_f32_e64 s[12:13], v229, v40
	v_addc_co_u32_e64 v231, s[18:19], 0, v231, s[14:15]
	v_cmp_ge_f32_e64 s[14:15], v198, v38
	v_addc_co_u32_e64 v231, s[18:19], 0, v231, s[16:17]
	v_cmp_ge_f32_e64 s[16:17], v199, v38
	v_addc_co_u32_e64 v231, s[18:19], 0, v231, s[12:13]
	v_cmp_ge_f32_e64 s[12:13], v200, v38
	v_addc_co_u32_e64 v232, s[18:19], 0, v232, s[14:15]
	v_cmp_ge_f32_e64 s[14:15], v201, v38
	v_addc_co_u32_e64 v232, s[18:19], 0, v232, s[16:17]
	v_cmp_ge_f32_e64 s[16:17], v202, v38
	v_addc_co_u32_e64 v232, s[18:19], 0, v232, s[12:13]
	v_cmp_ge_f32_e64 s[12:13], v203, v38
	v_addc_co_u32_e64 v232, s[18:19], 0, v232, s[14:15]
	v_cmp_ge_f32_e64 s[14:15], v204, v38
	v_addc_co_u32_e64 v232, s[18:19], 0, v232, s[16:17]
	v_cmp_ge_f32_e64 s[16:17], v205, v38
	v_addc_co_u32_e64 v232, s[18:19], 0, v232, s[12:13]
	v_cmp_gt_f32_e64 s[12:13], v206, v38
	v_cmp_ge_f32_e64 s[20:21], v206, v38
	s_and_b64 s[20:21], s[20:21], s[6:7]
	s_or_b64 s[12:13], s[12:13], s[20:21]
	v_addc_co_u32_e64 v232, s[18:19], 0, v232, s[14:15]
	v_cmp_gt_f32_e64 s[14:15], v207, v38
	v_cmp_ge_f32_e64 s[20:21], v207, v38
	s_and_b64 s[20:21], s[20:21], s[8:9]
	s_or_b64 s[14:15], s[14:15], s[20:21]
	v_addc_co_u32_e64 v232, s[18:19], 0, v232, s[16:17]
	v_cmp_gt_f32_e64 s[16:17], v208, v38
	v_cmp_ge_f32_e64 s[20:21], v208, v38
	s_and_b64 s[20:21], s[20:21], s[10:11]
	s_or_b64 s[16:17], s[16:17], s[20:21]
	v_addc_co_u32_e64 v232, s[18:19], 0, v232, s[12:13]
	v_cmp_gt_f32_e64 s[12:13], v209, v38
	v_addc_co_u32_e64 v232, s[18:19], 0, v232, s[14:15]
	v_cmp_gt_f32_e64 s[14:15], v210, v38
	v_addc_co_u32_e64 v232, s[18:19], 0, v232, s[16:17]
; DI int lane_get_i(int v, int srclane) { return __builtin_amdgcn_ds_bpermute(srclane << 2, v); }
; DI void attn_phase(const Params& p, const int layer, const int wid_s) {
;     ...
;       mk = 0;
; #pragma unroll
;       for (int nt = 0; nt < 8; ++nt) { const int ja = nt * 4 + fql; if (cnt[nt] < 8 && ja <= cur) mk |= 1u << ja; }
;       mk |= (unsigned)lane_get_i((int)mk, lane ^ 16);
;       mk |= (unsigned)lane_get_i((int)mk, lane ^ 32);
;       }
;       selmask = mk;
	v_cmp_gt_f32_e64 s[16:17], v211, v38
	v_addc_co_u32_e64 v232, s[18:19], 0, v232, s[12:13]
	v_cmp_gt_f32_e64 s[12:13], v212, v38
	v_addc_co_u32_e64 v232, s[18:19], 0, v232, s[14:15]
	v_cmp_gt_f32_e64 s[14:15], v213, v38
	v_addc_co_u32_e64 v232, s[18:19], 0, v232, s[16:17]
	v_cmp_gt_f32_e64 s[16:17], v214, v38
	v_addc_co_u32_e64 v232, s[18:19], 0, v232, s[12:13]
	v_cmp_gt_f32_e64 s[12:13], v215, v38
	v_addc_co_u32_e64 v232, s[18:19], 0, v232, s[14:15]
	v_cmp_gt_f32_e64 s[14:15], v216, v38
	v_addc_co_u32_e64 v232, s[18:19], 0, v232, s[16:17]
	v_cmp_gt_f32_e64 s[16:17], v217, v38
	v_addc_co_u32_e64 v232, s[18:19], 0, v232, s[12:13]
	v_cmp_gt_f32_e64 s[12:13], v218, v38
	v_addc_co_u32_e64 v232, s[18:19], 0, v232, s[14:15]
	v_cmp_gt_f32_e64 s[14:15], v219, v38
	v_addc_co_u32_e64 v232, s[18:19], 0, v232, s[16:17]
	v_cmp_gt_f32_e64 s[16:17], v220, v38
	v_addc_co_u32_e64 v232, s[18:19], 0, v232, s[12:13]
	v_cmp_gt_f32_e64 s[12:13], v221, v38
	v_addc_co_u32_e64 v232, s[18:19], 0, v232, s[14:15]
	v_cmp_gt_f32_e64 s[14:15], v222, v38
	v_addc_co_u32_e64 v232, s[18:19], 0, v232, s[16:17]
	v_cmp_gt_f32_e64 s[16:17], v223, v38
	v_addc_co_u32_e64 v232, s[18:19], 0, v232, s[12:13]
	v_cmp_gt_f32_e64 s[12:13], v224, v38
	v_addc_co_u32_e64 v232, s[18:19], 0, v232, s[14:15]
	v_cmp_gt_f32_e64 s[14:15], v225, v38
	v_addc_co_u32_e64 v232, s[18:19], 0, v232, s[16:17]
	v_cmp_gt_f32_e64 s[16:17], v226, v38
	v_addc_co_u32_e64 v232, s[18:19], 0, v232, s[12:13]
	v_cmp_gt_f32_e64 s[12:13], v227, v38
	v_addc_co_u32_e64 v232, s[18:19], 0, v232, s[14:15]
	v_cmp_gt_f32_e64 s[14:15], v228, v38
	v_addc_co_u32_e64 v232, s[18:19], 0, v232, s[16:17]
	v_cmp_gt_f32_e64 s[16:17], v229, v38
	v_addc_co_u32_e64 v232, s[18:19], 0, v232, s[12:13]
	v_cmp_ge_f32_e64 s[12:13], v198, v37
	v_addc_co_u32_e64 v232, s[18:19], 0, v232, s[14:15]
	v_cmp_ge_f32_e64 s[14:15], v199, v37
	v_addc_co_u32_e64 v232, s[18:19], 0, v232, s[16:17]
	v_cmp_ge_f32_e64 s[16:17], v200, v37
	v_addc_co_u32_e64 v233, s[18:19], 0, v233, s[12:13]
	v_cmp_ge_f32_e64 s[12:13], v201, v37
	v_addc_co_u32_e64 v233, s[18:19], 0, v233, s[14:15]
	v_cmp_ge_f32_e64 s[14:15], v202, v37
	v_addc_co_u32_e64 v233, s[18:19], 0, v233, s[16:17]
	v_cmp_ge_f32_e64 s[16:17], v203, v37
	v_addc_co_u32_e64 v233, s[18:19], 0, v233, s[12:13]
	v_cmp_ge_f32_e64 s[12:13], v204, v37
	v_addc_co_u32_e64 v233, s[18:19], 0, v233, s[14:15]
	v_cmp_ge_f32_e64 s[14:15], v205, v37
	v_addc_co_u32_e64 v233, s[18:19], 0, v233, s[16:17]
	v_cmp_ge_f32_e64 s[16:17], v206, v37
	v_addc_co_u32_e64 v233, s[18:19], 0, v233, s[12:13]
	v_cmp_ge_f32_e64 s[12:13], v207, v37
	v_addc_co_u32_e64 v233, s[18:19], 0, v233, s[14:15]
	v_cmp_ge_f32_e64 s[14:15], v208, v37
	v_addc_co_u32_e64 v233, s[18:19], 0, v233, s[16:17]
	v_cmp_ge_f32_e64 s[16:17], v209, v37
	v_addc_co_u32_e64 v233, s[18:19], 0, v233, s[12:13]
	v_cmp_gt_f32_e64 s[12:13], v210, v37
	v_cmp_ge_f32_e64 s[20:21], v210, v37
	s_and_b64 s[20:21], s[20:21], s[6:7]
	s_or_b64 s[12:13], s[12:13], s[20:21]
	v_addc_co_u32_e64 v233, s[18:19], 0, v233, s[14:15]
	v_cmp_gt_f32_e64 s[14:15], v211, v37
	v_cmp_ge_f32_e64 s[20:21], v211, v37
	s_and_b64 s[20:21], s[20:21], s[8:9]
	s_or_b64 s[14:15], s[14:15], s[20:21]
	v_addc_co_u32_e64 v233, s[18:19], 0, v233, s[16:17]
	v_cmp_gt_f32_e64 s[16:17], v212, v37
	v_cmp_ge_f32_e64 s[20:21], v212, v37
	s_and_b64 s[20:21], s[20:21], s[10:11]
	s_or_b64 s[16:17], s[16:17], s[20:21]
	v_addc_co_u32_e64 v233, s[18:19], 0, v233, s[12:13]
	v_cmp_gt_f32_e64 s[12:13], v213, v37
	v_addc_co_u32_e64 v233, s[18:19], 0, v233, s[14:15]
	v_cmp_gt_f32_e64 s[14:15], v214, v37
	v_addc_co_u32_e64 v233, s[18:19], 0, v233, s[16:17]
	v_cmp_gt_f32_e64 s[16:17], v215, v37
	v_addc_co_u32_e64 v233, s[18:19], 0, v233, s[12:13]
	v_cmp_gt_f32_e64 s[12:13], v216, v37
	v_addc_co_u32_e64 v233, s[18:19], 0, v233, s[14:15]
	v_cmp_gt_f32_e64 s[14:15], v217, v37
	v_addc_co_u32_e64 v233, s[18:19], 0, v233, s[16:17]
	v_cmp_gt_f32_e64 s[16:17], v218, v37
	v_addc_co_u32_e64 v233, s[18:19], 0, v233, s[12:13]
	v_cmp_gt_f32_e64 s[12:13], v219, v37
	v_addc_co_u32_e64 v233, s[18:19], 0, v233, s[14:15]
	v_cmp_gt_f32_e64 s[14:15], v220, v37
	v_addc_co_u32_e64 v233, s[18:19], 0, v233, s[16:17]
	v_cmp_gt_f32_e64 s[16:17], v221, v37
	v_addc_co_u32_e64 v233, s[18:19], 0, v233, s[12:13]
	v_cmp_gt_f32_e64 s[12:13], v222, v37
	v_addc_co_u32_e64 v233, s[18:19], 0, v233, s[14:15]
	v_cmp_gt_f32_e64 s[14:15], v223, v37
	v_addc_co_u32_e64 v233, s[18:19], 0, v233, s[16:17]
	v_cmp_gt_f32_e64 s[16:17], v224, v37
	v_addc_co_u32_e64 v233, s[18:19], 0, v233, s[12:13]
	v_cmp_gt_f32_e64 s[12:13], v225, v37
	v_addc_co_u32_e64 v233, s[18:19], 0, v233, s[14:15]
	v_cmp_gt_f32_e64 s[14:15], v226, v37
	v_addc_co_u32_e64 v233, s[18:19], 0, v233, s[16:17]
	v_cmp_gt_f32_e64 s[16:17], v227, v37
	v_addc_co_u32_e64 v233, s[18:19], 0, v233, s[12:13]
	v_cmp_gt_f32_e64 s[12:13], v228, v37
	v_addc_co_u32_e64 v233, s[18:19], 0, v233, s[14:15]
	v_cmp_gt_f32_e64 s[14:15], v229, v37
	v_addc_co_u32_e64 v233, s[18:19], 0, v233, s[16:17]
	s_nop 1
	v_addc_co_u32_e64 v233, s[18:19], 0, v233, s[12:13]
	v_addc_co_u32_e64 v233, s[18:19], 0, v233, s[14:15]
	v_cmp_gt_u32_e64 s[12:13], 8, v230
	v_cmp_ge_i32_e64 s[14:15], s54, v238
	v_lshlrev_b32_e64 v238, v238, 1
	s_and_b64 s[12:13], s[12:13], s[14:15]
	s_nop 1
	v_cndmask_b32_e64 v238, 0, v238, s[12:13]
	v_cmp_gt_u32_e64 s[16:17], 8, v231
	v_cmp_ge_i32_e64 s[20:21], s54, v239
	v_lshlrev_b32_e64 v239, v239, 1
	s_and_b64 s[16:17], s[16:17], s[20:21]
	s_nop 1
	v_cndmask_b32_e64 v239, 0, v239, s[16:17]
	v_cmp_gt_u32_e64 s[12:13], 8, v232
	v_cmp_ge_i32_e64 s[14:15], s54, v240
	v_lshlrev_b32_e64 v240, v240, 1
	s_and_b64 s[12:13], s[12:13], s[14:15]
	s_nop 1
	v_cndmask_b32_e64 v240, 0, v240, s[12:13]
	v_cmp_gt_u32_e64 s[16:17], 8, v233
	v_cmp_ge_i32_e64 s[20:21], s54, v241
	v_lshlrev_b32_e64 v241, v241, 1
	s_and_b64 s[16:17], s[16:17], s[20:21]
	s_nop 1
	v_cndmask_b32_e64 v241, 0, v241, s[16:17]
	v_or_b32_e32 v0, v238, v239
	v_or3_b32 v0, v0, v240, v241
.Lrk_join:
	ds_write_b32 v151, v0 offset:22656
	s_waitcnt lgkmcnt(0)
	s_barrier
	ds_read_b32 v2, v182 offset:22656
	s_waitcnt lgkmcnt(0)
	v_or_b32_e32 v0, v0, v2
	v_mov_b32_e32 v2, v0
	s_nop 1
	v_permlane16_swap_b32_e32 v2, v0
	v_or_b32_e32 v0, v0, v2
	v_mov_b32_e32 v2, v0
	s_nop 1
	v_permlane32_swap_b32_e32 v2, v0
	v_or_b32_e32 v5, v0, v2
